# v43 + the XCD leader no longer bumps the (now unread) per-XCD generation word after the barrier, so it skips one atomic and its wait
# baseline (speedup 1.0000x reference)
; __device__ __forceinline__ unsigned xb_add(unsigned* p, unsigned v) { return __hip_atomic_fetch_add(p, v, __ATOMIC_RELAXED, __HIP_MEMORY_SCOPE_AGENT); }
; __device__ __forceinline__ void xcd_barrier(const XcdBarrier& b) {
;     ...
;             __builtin_amdgcn_fence(__ATOMIC_ACQUIRE, "agent");
;             xb_add(&bar[XB_XGEN(b.x)], 1u);
;             asm volatile("s_waitcnt vmcnt(0)" ::: "memory");
.LBB0_600:
	s_or_b64 exec, exec, s[8:9]
	s_mov_b64 s[8:9], exec
	v_mbcnt_lo_u32_b32 v1, s8, 0
	v_mbcnt_hi_u32_b32 v1, s9, v1
	v_cmp_eq_u32_e32 vcc, 0, v1
	s_waitcnt vmcnt(0)
	buffer_inv sc1
	s_and_saveexec_b64 s[12:13], vcc
	s_cbranch_execz .LBB0_602
	s_bcnt1_i32_b64 s0, s[8:9]
	v_mov_b32_e32 v1, s0
	v_mov_b32_e32 v2, 0x2000
	s_nop 0

; __device__ __forceinline__ unsigned xb_add(unsigned* p, unsigned v) { return __hip_atomic_fetch_add(p, v, __ATOMIC_RELAXED, __HIP_MEMORY_SCOPE_AGENT); }
; __device__ __forceinline__ void xcd_barrier(const XcdBarrier& b) {
;     ...
;             __builtin_amdgcn_fence(__ATOMIC_ACQUIRE, "agent");
;             xb_add(&bar[XB_XGEN(b.x)], 1u);
;             asm volatile("s_waitcnt vmcnt(0)" ::: "memory");
.LBB0_661:
	s_or_b64 exec, exec, s[12:13]
	s_mov_b64 s[12:13], exec
	v_mbcnt_lo_u32_b32 v1, s12, 0
	v_mbcnt_hi_u32_b32 v1, s13, v1
	v_cmp_eq_u32_e32 vcc, 0, v1
	s_waitcnt vmcnt(0)
	buffer_inv sc1
	s_and_saveexec_b64 s[14:15], vcc
	s_cbranch_execz .LBB0_663
	s_bcnt1_i32_b64 s0, s[12:13]
	v_mov_b32_e32 v1, s0
	v_mov_b32_e32 v2, 0x2000
	s_nop 0

; __device__ __forceinline__ unsigned xb_add(unsigned* p, unsigned v) { return __hip_atomic_fetch_add(p, v, __ATOMIC_RELAXED, __HIP_MEMORY_SCOPE_AGENT); }
; __device__ __forceinline__ void xcd_barrier(const XcdBarrier& b) {
;     ...
;             __builtin_amdgcn_fence(__ATOMIC_ACQUIRE, "agent");
;             xb_add(&bar[XB_XGEN(b.x)], 1u);
;             asm volatile("s_waitcnt vmcnt(0)" ::: "memory");
.LBB0_1165:
	s_or_b64 exec, exec, s[8:9]
	s_mov_b64 s[8:9], exec
	v_mbcnt_lo_u32_b32 v1, s8, 0
	v_mbcnt_hi_u32_b32 v1, s9, v1
	v_cmp_eq_u32_e32 vcc, 0, v1
	s_waitcnt vmcnt(0)
	buffer_inv sc1
	s_and_saveexec_b64 s[10:11], vcc
	s_cbranch_execz .LBB0_1167
	s_bcnt1_i32_b64 s0, s[8:9]
	v_mov_b32_e32 v1, s0
	v_mov_b32_e32 v2, 0x2000
	s_nop 0

; __device__ __forceinline__ unsigned xb_add(unsigned* p, unsigned v) { return __hip_atomic_fetch_add(p, v, __ATOMIC_RELAXED, __HIP_MEMORY_SCOPE_AGENT); }
; __device__ __forceinline__ void xcd_barrier(const XcdBarrier& b) {
;     ...
;             __builtin_amdgcn_fence(__ATOMIC_ACQUIRE, "agent");
;             xb_add(&bar[XB_XGEN(b.x)], 1u);
;             asm volatile("s_waitcnt vmcnt(0)" ::: "memory");
.LBB0_2109:
	s_or_b64 exec, exec, s[6:7]
	s_mov_b64 s[6:7], exec
	v_mbcnt_lo_u32_b32 v1, s6, 0
	v_mbcnt_hi_u32_b32 v1, s7, v1
	v_cmp_eq_u32_e32 vcc, 0, v1
	s_waitcnt vmcnt(0)
	buffer_inv sc1
	s_and_saveexec_b64 s[8:9], vcc
	s_cbranch_execz .LBB0_2111
	s_bcnt1_i32_b64 s3, s[6:7]
	v_mov_b32_e32 v1, s3
	v_mov_b32_e32 v2, 0x2000
	s_nop 0

; __device__ __forceinline__ unsigned xb_add(unsigned* p, unsigned v) { return __hip_atomic_fetch_add(p, v, __ATOMIC_RELAXED, __HIP_MEMORY_SCOPE_AGENT); }
; __device__ __forceinline__ void xcd_barrier(const XcdBarrier& b) {
;     ...
;             __builtin_amdgcn_fence(__ATOMIC_ACQUIRE, "agent");
;             xb_add(&bar[XB_XGEN(b.x)], 1u);
;             asm volatile("s_waitcnt vmcnt(0)" ::: "memory");
.LBB0_2211:
	s_or_b64 exec, exec, s[8:9]
	s_mov_b64 s[8:9], exec
	v_mbcnt_lo_u32_b32 v1, s8, 0
	v_mbcnt_hi_u32_b32 v1, s9, v1
	v_cmp_eq_u32_e32 vcc, 0, v1
	s_waitcnt vmcnt(0)
	buffer_inv sc1
	s_and_saveexec_b64 s[10:11], vcc
	s_cbranch_execz .LBB0_2213
	s_bcnt1_i32_b64 s3, s[8:9]
	v_mov_b32_e32 v1, s3
	v_mov_b32_e32 v2, 0x2000
	s_nop 0

; __device__ __forceinline__ unsigned xb_add(unsigned* p, unsigned v) { return __hip_atomic_fetch_add(p, v, __ATOMIC_RELAXED, __HIP_MEMORY_SCOPE_AGENT); }
; __device__ __forceinline__ void xcd_barrier(const XcdBarrier& b) {
;     ...
;             __builtin_amdgcn_fence(__ATOMIC_ACQUIRE, "agent");
;             xb_add(&bar[XB_XGEN(b.x)], 1u);
;             asm volatile("s_waitcnt vmcnt(0)" ::: "memory");
.LBB0_2434:
	s_bcnt1_i32_b64 s3, s[6:7]
	v_mov_b32_e32 v1, s3
	v_mov_b32_e32 v2, 0x2000
	s_nop 0
	s_getpc_b64 s[98:99]
